# gate/up epilogue: Y stores widened to dwordx4 (n=0/n=1 column blocks exchanged between lane pairs with v_permlane16_swap), 8 stores per unit instead of 16
# speedup vs baseline: 1.0276x; 1.0053x over previous
; #define LAS __attribute__((address_space(3)))
;     DI void operator()(const AccT& acc, const Unit& u, int wr, int wc, int fr, int fq, LAS unsigned char* ldsx) const {
;     ...
;         for (int n = 0; n < 2; ++n) {
;             const int f = u.pn * 128 + wc * 32 + 16 * n + 4 * fq;
; #pragma unroll
;             for (int ai = 0; ai < 2; ++ai) {
;                 f32x4 hm1 = {0.f, 0.f, 0.f, 0.f}, hm2 = {0.f, 0.f, 0.f, 0.f};
;                 const int sb = 4 * (T - GU_PT) + 2 * ai + wr;
;                 if (prompt) {
;                     if (ai | wr) { const int sai = wr ? ai : ai - 1, swr = wr ^ 1; const LAS float* hp = H + ((sai * 2 + swr) * 4 + wc) * 64 + 16 * n + 4 * fq;
;                         hm2 = *(const LAS f32x4*)hp; hm1 = *(const LAS f32x4*)(hp + 32); }
;                 } else { hm2 = *(const f32x4*)(state + (size_t)(sb * 2) * DFF + f); hm1 = *(const f32x4*)(state + (size_t)(sb * 2 + 1) * DFF + f); }
;                 f32x4 p1 = hm1, p2;
; #pragma unroll
;                 for (int j = 0; j < 4; ++j) p2[j] = fr == 1 ? hm1[j] : hm2[j];
; #pragma unroll
;                 for (int m = 0; m < 4; ++m) {
;                     const f32x4 g = acc[ai][0][m][n] * rs[ai][m];
;                     f32x4 gm1, gm2;
; #pragma unroll
;                     for (int j = 0; j < 4; ++j) {
;                         gm1[j] = __int_as_float(__builtin_amdgcn_update_dpp(__float_as_int(p1[j]), __float_as_int(g[j]), 0x111, 0xf, 0xf, false));
;                         gm2[j] = __int_as_float(__builtin_amdgcn_update_dpp(__float_as_int(p2[j]), __float_as_int(g[j]), 0x112, 0xf, 0xf, false));
;                         if (m < 3) {
;                             p1[j] = __int_as_float(__builtin_amdgcn_update_dpp(0, __float_as_int(g[j]), 0x121, 0xf, 0xf, false));
;                             p2[j] = __int_as_float(__builtin_amdgcn_update_dpp(0, __float_as_int(g[j]), 0x122, 0xf, 0xf, false)); }
;                     }
;                     const f32x4 cv = cb[n] + w0[n] * gm2 + w1[n] * gm1 + w2[n] * g;
;                     const f32x4 up = acc[ai][1][m][n] * rs[ai][m];
;                     f32x4 y;
; #pragma unroll
;                     for (int j = 0; j < 4; ++j) y[j] = cv[j] * __builtin_amdgcn_rcpf(1.f + __builtin_amdgcn_exp2f(-cv[j] * LOG2E)) * up[j];
;                     const int tok = tok0 + 128 * ai + 16 * m;
;                     bool ok = true;
.Lgu_samp0:
	v_add_u32_e32 v213, 16, v172
	s_add_u32 s46, s54, 0xfffea000
	s_addc_u32 s47, s55, -1
	v_mul_lo_u32 v213, v213, s87
	v_cndmask_b32_e64 v160, 0, v124, s[94:95]
	v_cndmask_b32_e64 v124, v124, 0, s[94:95]
	v_cndmask_b32_e64 v164, 0, v132, s[96:97]
	v_cndmask_b32_e64 v132, v132, 0, s[96:97]
	v_cndmask_b32_e64 v161, 0, v125, s[94:95]
	v_cndmask_b32_e64 v125, v125, 0, s[94:95]
	v_cndmask_b32_e64 v165, 0, v133, s[96:97]
	v_cndmask_b32_e64 v133, v133, 0, s[96:97]
	v_cndmask_b32_e64 v162, 0, v126, s[94:95]
	v_cndmask_b32_e64 v126, v126, 0, s[94:95]
	v_cndmask_b32_e64 v166, 0, v134, s[96:97]
	v_cndmask_b32_e64 v134, v134, 0, s[96:97]
	v_cndmask_b32_e64 v163, 0, v127, s[94:95]
	v_cndmask_b32_e64 v127, v127, 0, s[94:95]
	v_cndmask_b32_e64 v167, 0, v135, s[96:97]
	v_cndmask_b32_e64 v135, v135, 0, s[96:97]
	v_add_lshl_u32 v213, v213, v216, 1
	v_and_b32_e32 v186, 16, v226
	v_lshrrev_b32_e32 v187, 1, v186
	v_add3_u32 v213, v213, v186, v187
	v_pk_mul_f32 v[156:157], v[156:157], v[214:215] op_sel_hi:[1,0]
	v_pk_mul_f32 v[158:159], v[158:159], v[214:215] op_sel_hi:[1,0]
	v_pk_mul_f32 v[152:153], v[152:153], v[214:215] op_sel_hi:[1,0]
	v_pk_mul_f32 v[154:155], v[154:155], v[214:215] op_sel_hi:[1,0]
	v_pk_fma_f32 v[218:219], v[128:129], v[156:157], v[136:137]
	v_pk_fma_f32 v[220:221], v[130:131], v[158:159], v[138:139]
	v_fmac_f32_dpp v218, v156, v124 row_ror:1 row_mask:0xf bank_mask:0xf
	v_fmac_f32_dpp v219, v157, v125 row_ror:1 row_mask:0xf bank_mask:0xf
	v_fmac_f32_dpp v220, v158, v126 row_ror:1 row_mask:0xf bank_mask:0xf
	v_fmac_f32_dpp v221, v159, v127 row_ror:1 row_mask:0xf bank_mask:0xf
	v_fmac_f32_dpp v218, v156, v132 row_ror:2 row_mask:0xf bank_mask:0xf
	v_fmac_f32_dpp v219, v157, v133 row_ror:2 row_mask:0xf bank_mask:0xf
	v_fmac_f32_dpp v220, v158, v134 row_ror:2 row_mask:0xf bank_mask:0xf
	v_fmac_f32_dpp v221, v159, v135 row_ror:2 row_mask:0xf bank_mask:0xf
	s_waitcnt lgkmcnt(0)
	v_fmac_f32_e32 v218, v248, v160
	v_fmac_f32_e32 v219, v249, v161
	v_fmac_f32_e32 v220, v250, v162
	v_fmac_f32_e32 v221, v251, v163
	v_fmac_f32_dpp v218, v248, v164 row_ror:14 row_mask:0xf bank_mask:0xf
	v_fmac_f32_dpp v219, v249, v165 row_ror:14 row_mask:0xf bank_mask:0xf
	v_fmac_f32_dpp v220, v250, v166 row_ror:14 row_mask:0xf bank_mask:0xf
	v_fmac_f32_dpp v221, v251, v167 row_ror:14 row_mask:0xf bank_mask:0xf
	v_pk_mul_f32 v[204:205], v[218:219], v[184:185] op_sel:[0,1] op_sel_hi:[1,1]
	v_pk_mul_f32 v[148:149], v[148:149], v[210:211] op_sel_hi:[1,0]
	v_pk_mul_f32 v[206:207], v[220:221], v[184:185] op_sel:[0,1] op_sel_hi:[1,1]
	v_pk_mul_f32 v[150:151], v[150:151], v[210:211] op_sel_hi:[1,0]
	v_exp_f32_e32 v204, v204
	v_pk_mul_f32 v[144:145], v[144:145], v[210:211] op_sel_hi:[1,0]
	v_exp_f32_e32 v205, v205
	v_pk_mul_f32 v[146:147], v[146:147], v[210:211] op_sel_hi:[1,0]
	v_exp_f32_e32 v206, v206
	v_pk_fma_f32 v[222:223], v[128:129], v[148:149], v[136:137]
	v_exp_f32_e32 v207, v207
	v_pk_fma_f32 v[224:225], v[130:131], v[150:151], v[138:139]
	v_pk_add_f32 v[204:205], v[204:205], 1.0 op_sel_hi:[1,0]
	v_fmac_f32_dpp v222, v148, v124 row_ror:1 row_mask:0xf bank_mask:0xf
	v_pk_add_f32 v[206:207], v[206:207], 1.0 op_sel_hi:[1,0]
	v_fmac_f32_dpp v223, v149, v125 row_ror:1 row_mask:0xf bank_mask:0xf
	v_rcp_f32_e32 v204, v204
	v_fmac_f32_dpp v224, v150, v126 row_ror:1 row_mask:0xf bank_mask:0xf
	v_rcp_f32_e32 v205, v205
	v_fmac_f32_dpp v225, v151, v127 row_ror:1 row_mask:0xf bank_mask:0xf
	v_rcp_f32_e32 v206, v206
	v_fmac_f32_dpp v222, v148, v132 row_ror:2 row_mask:0xf bank_mask:0xf
	v_rcp_f32_e32 v207, v207
	v_fmac_f32_dpp v223, v149, v133 row_ror:2 row_mask:0xf bank_mask:0xf
	v_pk_mul_f32 v[218:219], v[218:219], v[204:205]
	v_fmac_f32_dpp v224, v150, v134 row_ror:2 row_mask:0xf bank_mask:0xf
	v_pk_mul_f32 v[220:221], v[220:221], v[206:207]
	v_fmac_f32_dpp v225, v151, v135 row_ror:2 row_mask:0xf bank_mask:0xf
	v_pk_mul_f32 v[152:153], v[152:153], v[218:219]
	v_fmac_f32_dpp v222, v156, v160 row_ror:1 row_mask:0xf bank_mask:0xf
	v_pk_mul_f32 v[154:155], v[154:155], v[220:221]
	v_fmac_f32_dpp v223, v157, v161 row_ror:1 row_mask:0xf bank_mask:0xf
	v_cvt_pk_bf16_f32 v152, v152, v153
	v_fmac_f32_dpp v224, v158, v162 row_ror:1 row_mask:0xf bank_mask:0xf
	v_cvt_pk_bf16_f32 v153, v154, v155
	v_fmac_f32_dpp v225, v159, v163 row_ror:1 row_mask:0xf bank_mask:0xf
	v_fmac_f32_dpp v222, v156, v164 row_ror:2 row_mask:0xf bank_mask:0xf
	v_fmac_f32_dpp v223, v157, v165 row_ror:2 row_mask:0xf bank_mask:0xf
	v_fmac_f32_dpp v224, v158, v166 row_ror:2 row_mask:0xf bank_mask:0xf
	v_fmac_f32_dpp v225, v159, v167 row_ror:2 row_mask:0xf bank_mask:0xf
	v_pk_mul_f32 v[204:205], v[222:223], v[184:185] op_sel:[0,1] op_sel_hi:[1,1]
	v_pk_mul_f32 v[140:141], v[140:141], v[208:209] op_sel_hi:[1,0]
	v_pk_mul_f32 v[206:207], v[224:225], v[184:185] op_sel:[0,1] op_sel_hi:[1,1]
	v_pk_mul_f32 v[142:143], v[142:143], v[208:209] op_sel_hi:[1,0]
	v_exp_f32_e32 v204, v204
	v_pk_mul_f32 v[120:121], v[120:121], v[208:209] op_sel_hi:[1,0]
	v_exp_f32_e32 v205, v205
	v_pk_mul_f32 v[122:123], v[122:123], v[208:209] op_sel_hi:[1,0]
	v_exp_f32_e32 v206, v206
	v_pk_fma_f32 v[218:219], v[128:129], v[140:141], v[136:137]
	v_exp_f32_e32 v207, v207
	v_pk_fma_f32 v[220:221], v[130:131], v[142:143], v[138:139]
	v_pk_add_f32 v[204:205], v[204:205], 1.0 op_sel_hi:[1,0]
	v_fmac_f32_dpp v218, v140, v124 row_ror:1 row_mask:0xf bank_mask:0xf
	v_pk_add_f32 v[206:207], v[206:207], 1.0 op_sel_hi:[1,0]
	v_fmac_f32_dpp v219, v141, v125 row_ror:1 row_mask:0xf bank_mask:0xf
	v_rcp_f32_e32 v204, v204
	v_fmac_f32_dpp v220, v142, v126 row_ror:1 row_mask:0xf bank_mask:0xf
	v_rcp_f32_e32 v205, v205
	v_fmac_f32_dpp v221, v143, v127 row_ror:1 row_mask:0xf bank_mask:0xf
; DI u32x2 pk4(f32x4 v) { u32x2 r; r.x = pk2(v[0], v[1]); r.y = pk2(v[2], v[3]); return r; }
;     DI void operator()(const AccT& acc, const Unit& u, int wr, int wc, int fr, int fq, LAS unsigned char* ldsx) const {
;     ...
;                 for (int m = 0; m < 4; ++m) {
;                     const f32x4 g = acc[ai][0][m][n] * rs[ai][m];
;                     f32x4 gm1, gm2;
; #pragma unroll
;                     for (int j = 0; j < 4; ++j) {
;                         gm1[j] = __int_as_float(__builtin_amdgcn_update_dpp(__float_as_int(p1[j]), __float_as_int(g[j]), 0x111, 0xf, 0xf, false));
;                         gm2[j] = __int_as_float(__builtin_amdgcn_update_dpp(__float_as_int(p2[j]), __float_as_int(g[j]), 0x112, 0xf, 0xf, false));
;                         if (m < 3) {
;                             p1[j] = __int_as_float(__builtin_amdgcn_update_dpp(0, __float_as_int(g[j]), 0x121, 0xf, 0xf, false));
;                             p2[j] = __int_as_float(__builtin_amdgcn_update_dpp(0, __float_as_int(g[j]), 0x122, 0xf, 0xf, false)); }
;                     }
;                     const f32x4 cv = cb[n] + w0[n] * gm2 + w1[n] * gm1 + w2[n] * g;
;                     const f32x4 up = acc[ai][1][m][n] * rs[ai][m];
;                     f32x4 y;
; #pragma unroll
;                     for (int j = 0; j < 4; ++j) y[j] = cv[j] * __builtin_amdgcn_rcpf(1.f + __builtin_amdgcn_exp2f(-cv[j] * LOG2E)) * up[j];
;                     const int tok = tok0 + 128 * ai + 16 * m;
;                     bool ok = true;
;                     if (prompt && ai == 0 && m == 0) ok = (64 * wr + fr) >= 2;
;                     if (lastT) ok = ok && tok < SEQ;
;                     if (ok) *(u32x2*)(Y + ((unsigned)tok * (unsigned)DFF + (unsigned)f)) = pk4(y);
	v_rcp_f32_e32 v206, v206
	v_fmac_f32_dpp v218, v140, v132 row_ror:2 row_mask:0xf bank_mask:0xf
	v_rcp_f32_e32 v207, v207
	v_fmac_f32_dpp v219, v141, v133 row_ror:2 row_mask:0xf bank_mask:0xf
	v_pk_mul_f32 v[222:223], v[222:223], v[204:205]
	v_fmac_f32_dpp v220, v142, v134 row_ror:2 row_mask:0xf bank_mask:0xf
	v_pk_mul_f32 v[224:225], v[224:225], v[206:207]
	v_fmac_f32_dpp v221, v143, v135 row_ror:2 row_mask:0xf bank_mask:0xf
	v_pk_mul_f32 v[144:145], v[144:145], v[222:223]
	v_fmac_f32_dpp v218, v148, v160 row_ror:1 row_mask:0xf bank_mask:0xf
	v_pk_mul_f32 v[146:147], v[146:147], v[224:225]
	v_fmac_f32_dpp v219, v149, v161 row_ror:1 row_mask:0xf bank_mask:0xf
	v_cvt_pk_bf16_f32 v144, v144, v145
	v_fmac_f32_dpp v220, v150, v162 row_ror:1 row_mask:0xf bank_mask:0xf
	v_cvt_pk_bf16_f32 v145, v146, v147
	v_fmac_f32_dpp v221, v151, v163 row_ror:1 row_mask:0xf bank_mask:0xf
	v_fmac_f32_dpp v218, v148, v164 row_ror:2 row_mask:0xf bank_mask:0xf
	v_fmac_f32_dpp v219, v149, v165 row_ror:2 row_mask:0xf bank_mask:0xf
	v_fmac_f32_dpp v220, v150, v166 row_ror:2 row_mask:0xf bank_mask:0xf
	v_fmac_f32_dpp v221, v151, v167 row_ror:2 row_mask:0xf bank_mask:0xf
	v_pk_mul_f32 v[204:205], v[218:219], v[184:185] op_sel:[0,1] op_sel_hi:[1,1]
	v_pk_mul_f32 v[116:117], v[116:117], v[202:203] op_sel_hi:[1,0]
	v_pk_mul_f32 v[206:207], v[220:221], v[184:185] op_sel:[0,1] op_sel_hi:[1,1]
	v_pk_mul_f32 v[118:119], v[118:119], v[202:203] op_sel_hi:[1,0]
	v_exp_f32_e32 v204, v204
	v_pk_mul_f32 v[112:113], v[112:113], v[202:203] op_sel_hi:[1,0]
	v_exp_f32_e32 v205, v205
	v_pk_mul_f32 v[114:115], v[114:115], v[202:203] op_sel_hi:[1,0]
	v_exp_f32_e32 v206, v206
	v_pk_fma_f32 v[222:223], v[128:129], v[116:117], v[136:137]
	v_exp_f32_e32 v207, v207
	v_pk_fma_f32 v[224:225], v[130:131], v[118:119], v[138:139]
	v_pk_add_f32 v[204:205], v[204:205], 1.0 op_sel_hi:[1,0]
	v_fmac_f32_dpp v222, v116, v124 row_ror:1 row_mask:0xf bank_mask:0xf
	v_pk_add_f32 v[206:207], v[206:207], 1.0 op_sel_hi:[1,0]
	v_fmac_f32_dpp v223, v117, v125 row_ror:1 row_mask:0xf bank_mask:0xf
	v_rcp_f32_e32 v204, v204
	v_fmac_f32_dpp v224, v118, v126 row_ror:1 row_mask:0xf bank_mask:0xf
	v_rcp_f32_e32 v205, v205
	v_fmac_f32_dpp v225, v119, v127 row_ror:1 row_mask:0xf bank_mask:0xf
	v_rcp_f32_e32 v206, v206
	v_fmac_f32_dpp v222, v116, v132 row_ror:2 row_mask:0xf bank_mask:0xf
	v_rcp_f32_e32 v207, v207
	v_fmac_f32_dpp v223, v117, v133 row_ror:2 row_mask:0xf bank_mask:0xf
	v_pk_mul_f32 v[218:219], v[218:219], v[204:205]
	v_fmac_f32_dpp v224, v118, v134 row_ror:2 row_mask:0xf bank_mask:0xf
	v_pk_mul_f32 v[220:221], v[220:221], v[206:207]
	v_fmac_f32_dpp v225, v119, v135 row_ror:2 row_mask:0xf bank_mask:0xf
	v_pk_mul_f32 v[120:121], v[120:121], v[218:219]
	v_fmac_f32_dpp v222, v140, v160 row_ror:1 row_mask:0xf bank_mask:0xf
	v_pk_mul_f32 v[122:123], v[122:123], v[220:221]
	v_fmac_f32_dpp v223, v141, v161 row_ror:1 row_mask:0xf bank_mask:0xf
	v_cvt_pk_bf16_f32 v120, v120, v121
	v_fmac_f32_dpp v224, v142, v162 row_ror:1 row_mask:0xf bank_mask:0xf
	v_cvt_pk_bf16_f32 v121, v122, v123
	v_fmac_f32_dpp v225, v143, v163 row_ror:1 row_mask:0xf bank_mask:0xf
	v_fmac_f32_dpp v222, v140, v164 row_ror:2 row_mask:0xf bank_mask:0xf
	v_fmac_f32_dpp v223, v141, v165 row_ror:2 row_mask:0xf bank_mask:0xf
	v_fmac_f32_dpp v224, v142, v166 row_ror:2 row_mask:0xf bank_mask:0xf
	v_fmac_f32_dpp v225, v143, v167 row_ror:2 row_mask:0xf bank_mask:0xf
	v_pk_mul_f32 v[204:205], v[222:223], v[184:185] op_sel:[0,1] op_sel_hi:[1,1]
	v_pk_mul_f32 v[108:109], v[108:109], v[200:201] op_sel_hi:[1,0]
	v_pk_mul_f32 v[206:207], v[224:225], v[184:185] op_sel:[0,1] op_sel_hi:[1,1]
	v_pk_mul_f32 v[110:111], v[110:111], v[200:201] op_sel_hi:[1,0]
	v_exp_f32_e32 v204, v204
	v_pk_mul_f32 v[104:105], v[104:105], v[200:201] op_sel_hi:[1,0]
	v_exp_f32_e32 v205, v205
	v_pk_mul_f32 v[106:107], v[106:107], v[200:201] op_sel_hi:[1,0]
	v_exp_f32_e32 v206, v206
	v_pk_fma_f32 v[218:219], v[128:129], v[108:109], v[136:137]
	v_exp_f32_e32 v207, v207
	v_pk_fma_f32 v[220:221], v[130:131], v[110:111], v[138:139]
	v_pk_add_f32 v[204:205], v[204:205], 1.0 op_sel_hi:[1,0]
	v_fmac_f32_dpp v218, v108, v124 row_ror:1 row_mask:0xf bank_mask:0xf
	v_pk_add_f32 v[206:207], v[206:207], 1.0 op_sel_hi:[1,0]
	v_fmac_f32_dpp v219, v109, v125 row_ror:1 row_mask:0xf bank_mask:0xf
	v_rcp_f32_e32 v204, v204
	v_fmac_f32_dpp v220, v110, v126 row_ror:1 row_mask:0xf bank_mask:0xf
	v_rcp_f32_e32 v205, v205
	v_fmac_f32_dpp v221, v111, v127 row_ror:1 row_mask:0xf bank_mask:0xf
	v_rcp_f32_e32 v206, v206
	v_fmac_f32_dpp v218, v108, v132 row_ror:2 row_mask:0xf bank_mask:0xf
	v_rcp_f32_e32 v207, v207
	v_fmac_f32_dpp v219, v109, v133 row_ror:2 row_mask:0xf bank_mask:0xf
	v_pk_mul_f32 v[222:223], v[222:223], v[204:205]
	v_fmac_f32_dpp v220, v110, v134 row_ror:2 row_mask:0xf bank_mask:0xf
	v_pk_mul_f32 v[224:225], v[224:225], v[206:207]
	v_fmac_f32_dpp v221, v111, v135 row_ror:2 row_mask:0xf bank_mask:0xf
	v_pk_mul_f32 v[112:113], v[112:113], v[222:223]
	v_fmac_f32_dpp v218, v248, v160 row_ror:12 row_mask:0xf bank_mask:0xf
	v_pk_mul_f32 v[114:115], v[114:115], v[224:225]
	v_fmac_f32_dpp v219, v249, v161 row_ror:12 row_mask:0xf bank_mask:0xf
	v_cvt_pk_bf16_f32 v112, v112, v113
	v_fmac_f32_dpp v220, v250, v162 row_ror:12 row_mask:0xf bank_mask:0xf
	v_cvt_pk_bf16_f32 v113, v114, v115
	v_fmac_f32_dpp v221, v251, v163 row_ror:12 row_mask:0xf bank_mask:0xf
	v_fmac_f32_dpp v218, v248, v164 row_ror:10 row_mask:0xf bank_mask:0xf
	v_fmac_f32_dpp v219, v249, v165 row_ror:10 row_mask:0xf bank_mask:0xf
	v_fmac_f32_dpp v220, v250, v166 row_ror:10 row_mask:0xf bank_mask:0xf
	v_fmac_f32_dpp v221, v251, v167 row_ror:10 row_mask:0xf bank_mask:0xf
; DI u32x2 pk4(f32x4 v) { u32x2 r; r.x = pk2(v[0], v[1]); r.y = pk2(v[2], v[3]); return r; }
;     DI void operator()(const AccT& acc, const Unit& u, int wr, int wc, int fr, int fq, LAS unsigned char* ldsx) const {
;     ...
;                 for (int m = 0; m < 4; ++m) {
;                     const f32x4 g = acc[ai][0][m][n] * rs[ai][m];
;                     f32x4 gm1, gm2;
; #pragma unroll
;                     for (int j = 0; j < 4; ++j) {
;                         gm1[j] = __int_as_float(__builtin_amdgcn_update_dpp(__float_as_int(p1[j]), __float_as_int(g[j]), 0x111, 0xf, 0xf, false));
;                         gm2[j] = __int_as_float(__builtin_amdgcn_update_dpp(__float_as_int(p2[j]), __float_as_int(g[j]), 0x112, 0xf, 0xf, false));
;                         if (m < 3) {
;                             p1[j] = __int_as_float(__builtin_amdgcn_update_dpp(0, __float_as_int(g[j]), 0x121, 0xf, 0xf, false));
;                             p2[j] = __int_as_float(__builtin_amdgcn_update_dpp(0, __float_as_int(g[j]), 0x122, 0xf, 0xf, false)); }
;                     }
;                     const f32x4 cv = cb[n] + w0[n] * gm2 + w1[n] * gm1 + w2[n] * g;
;                     const f32x4 up = acc[ai][1][m][n] * rs[ai][m];
;                     f32x4 y;
; #pragma unroll
;                     for (int j = 0; j < 4; ++j) y[j] = cv[j] * __builtin_amdgcn_rcpf(1.f + __builtin_amdgcn_exp2f(-cv[j] * LOG2E)) * up[j];
;                     const int tok = tok0 + 128 * ai + 16 * m;
;                     bool ok = true;
;                     if (prompt && ai == 0 && m == 0) ok = (64 * wr + fr) >= 2;
;                     if (lastT) ok = ok && tok < SEQ;
;                     if (ok) *(u32x2*)(Y + ((unsigned)tok * (unsigned)DFF + (unsigned)f)) = pk4(y);
	v_pk_mul_f32 v[204:205], v[218:219], v[184:185] op_sel:[0,1] op_sel_hi:[1,1]
	v_pk_mul_f32 v[100:101], v[100:101], v[192:193] op_sel_hi:[1,0]
	v_pk_mul_f32 v[206:207], v[220:221], v[184:185] op_sel:[0,1] op_sel_hi:[1,1]
	v_pk_mul_f32 v[102:103], v[102:103], v[192:193] op_sel_hi:[1,0]
	v_exp_f32_e32 v204, v204
	v_pk_mul_f32 v[96:97], v[96:97], v[192:193] op_sel_hi:[1,0]
	v_exp_f32_e32 v205, v205
	v_pk_mul_f32 v[98:99], v[98:99], v[192:193] op_sel_hi:[1,0]
	v_exp_f32_e32 v206, v206
	v_pk_fma_f32 v[222:223], v[128:129], v[100:101], v[136:137]
	v_exp_f32_e32 v207, v207
	v_pk_fma_f32 v[224:225], v[130:131], v[102:103], v[138:139]
	v_pk_add_f32 v[204:205], v[204:205], 1.0 op_sel_hi:[1,0]
	v_fmac_f32_dpp v222, v100, v124 row_ror:1 row_mask:0xf bank_mask:0xf
	v_pk_add_f32 v[206:207], v[206:207], 1.0 op_sel_hi:[1,0]
	v_fmac_f32_dpp v223, v101, v125 row_ror:1 row_mask:0xf bank_mask:0xf
	v_rcp_f32_e32 v204, v204
	v_fmac_f32_dpp v224, v102, v126 row_ror:1 row_mask:0xf bank_mask:0xf
	v_rcp_f32_e32 v205, v205
	v_fmac_f32_dpp v225, v103, v127 row_ror:1 row_mask:0xf bank_mask:0xf
	v_rcp_f32_e32 v206, v206
	v_fmac_f32_dpp v222, v100, v132 row_ror:2 row_mask:0xf bank_mask:0xf
	v_rcp_f32_e32 v207, v207
	v_fmac_f32_dpp v223, v101, v133 row_ror:2 row_mask:0xf bank_mask:0xf
	v_pk_mul_f32 v[218:219], v[218:219], v[204:205]
	v_fmac_f32_dpp v224, v102, v134 row_ror:2 row_mask:0xf bank_mask:0xf
	v_pk_mul_f32 v[220:221], v[220:221], v[206:207]
	v_fmac_f32_dpp v225, v103, v135 row_ror:2 row_mask:0xf bank_mask:0xf
	v_pk_mul_f32 v[104:105], v[104:105], v[218:219]
	v_fmac_f32_dpp v222, v108, v160 row_ror:1 row_mask:0xf bank_mask:0xf
	v_pk_mul_f32 v[106:107], v[106:107], v[220:221]
	v_fmac_f32_dpp v223, v109, v161 row_ror:1 row_mask:0xf bank_mask:0xf
	v_cvt_pk_bf16_f32 v104, v104, v105
	v_fmac_f32_dpp v224, v110, v162 row_ror:1 row_mask:0xf bank_mask:0xf
	v_cvt_pk_bf16_f32 v105, v106, v107
	v_fmac_f32_dpp v225, v111, v163 row_ror:1 row_mask:0xf bank_mask:0xf
	v_fmac_f32_dpp v222, v108, v164 row_ror:2 row_mask:0xf bank_mask:0xf
	v_fmac_f32_dpp v223, v109, v165 row_ror:2 row_mask:0xf bank_mask:0xf
	v_fmac_f32_dpp v224, v110, v166 row_ror:2 row_mask:0xf bank_mask:0xf
	v_fmac_f32_dpp v225, v111, v167 row_ror:2 row_mask:0xf bank_mask:0xf
	v_pk_mul_f32 v[204:205], v[222:223], v[184:185] op_sel:[0,1] op_sel_hi:[1,1]
	v_pk_mul_f32 v[92:93], v[92:93], v[190:191] op_sel_hi:[1,0]
	v_pk_mul_f32 v[206:207], v[224:225], v[184:185] op_sel:[0,1] op_sel_hi:[1,1]
	v_pk_mul_f32 v[94:95], v[94:95], v[190:191] op_sel_hi:[1,0]
	v_exp_f32_e32 v204, v204
	v_pk_mul_f32 v[88:89], v[88:89], v[190:191] op_sel_hi:[1,0]
	v_exp_f32_e32 v205, v205
	v_pk_mul_f32 v[90:91], v[90:91], v[190:191] op_sel_hi:[1,0]
	v_exp_f32_e32 v206, v206
	v_pk_fma_f32 v[218:219], v[128:129], v[92:93], v[136:137]
	v_exp_f32_e32 v207, v207
	v_pk_fma_f32 v[220:221], v[130:131], v[94:95], v[138:139]
	v_pk_add_f32 v[204:205], v[204:205], 1.0 op_sel_hi:[1,0]
	v_fmac_f32_dpp v218, v92, v124 row_ror:1 row_mask:0xf bank_mask:0xf
	v_pk_add_f32 v[206:207], v[206:207], 1.0 op_sel_hi:[1,0]
	v_fmac_f32_dpp v219, v93, v125 row_ror:1 row_mask:0xf bank_mask:0xf
	v_rcp_f32_e32 v204, v204
	v_fmac_f32_dpp v220, v94, v126 row_ror:1 row_mask:0xf bank_mask:0xf
	v_rcp_f32_e32 v205, v205
	v_fmac_f32_dpp v221, v95, v127 row_ror:1 row_mask:0xf bank_mask:0xf
	v_rcp_f32_e32 v206, v206
	v_fmac_f32_dpp v218, v92, v132 row_ror:2 row_mask:0xf bank_mask:0xf
	v_rcp_f32_e32 v207, v207
	v_fmac_f32_dpp v219, v93, v133 row_ror:2 row_mask:0xf bank_mask:0xf
	v_pk_mul_f32 v[222:223], v[222:223], v[204:205]
	v_fmac_f32_dpp v220, v94, v134 row_ror:2 row_mask:0xf bank_mask:0xf
	v_pk_mul_f32 v[224:225], v[224:225], v[206:207]
	v_fmac_f32_dpp v221, v95, v135 row_ror:2 row_mask:0xf bank_mask:0xf
	v_pk_mul_f32 v[96:97], v[96:97], v[222:223]
	v_fmac_f32_dpp v218, v100, v160 row_ror:1 row_mask:0xf bank_mask:0xf
	v_pk_mul_f32 v[98:99], v[98:99], v[224:225]
	v_fmac_f32_dpp v219, v101, v161 row_ror:1 row_mask:0xf bank_mask:0xf
	v_cvt_pk_bf16_f32 v96, v96, v97
	v_fmac_f32_dpp v220, v102, v162 row_ror:1 row_mask:0xf bank_mask:0xf
	v_cvt_pk_bf16_f32 v97, v98, v99
	v_fmac_f32_dpp v221, v103, v163 row_ror:1 row_mask:0xf bank_mask:0xf
	v_fmac_f32_dpp v218, v100, v164 row_ror:2 row_mask:0xf bank_mask:0xf
	v_fmac_f32_dpp v219, v101, v165 row_ror:2 row_mask:0xf bank_mask:0xf
	v_fmac_f32_dpp v220, v102, v166 row_ror:2 row_mask:0xf bank_mask:0xf
	v_fmac_f32_dpp v221, v103, v167 row_ror:2 row_mask:0xf bank_mask:0xf
	v_pk_mul_f32 v[204:205], v[218:219], v[184:185] op_sel:[0,1] op_sel_hi:[1,1]
	v_pk_mul_f32 v[84:85], v[84:85], v[184:185] op_sel_hi:[1,0]
	v_pk_mul_f32 v[206:207], v[220:221], v[184:185] op_sel:[0,1] op_sel_hi:[1,1]
	v_pk_mul_f32 v[86:87], v[86:87], v[184:185] op_sel_hi:[1,0]
	v_exp_f32_e32 v204, v204
	v_pk_mul_f32 v[80:81], v[80:81], v[184:185] op_sel_hi:[1,0]
	v_exp_f32_e32 v205, v205
	v_pk_mul_f32 v[82:83], v[82:83], v[184:185] op_sel_hi:[1,0]
	v_exp_f32_e32 v206, v206
	v_pk_fma_f32 v[222:223], v[128:129], v[84:85], v[136:137]
	v_exp_f32_e32 v207, v207
	v_pk_fma_f32 v[224:225], v[130:131], v[86:87], v[138:139]
	v_pk_add_f32 v[204:205], v[204:205], 1.0 op_sel_hi:[1,0]
	v_fmac_f32_dpp v222, v84, v124 row_ror:1 row_mask:0xf bank_mask:0xf
	v_pk_add_f32 v[206:207], v[206:207], 1.0 op_sel_hi:[1,0]
	v_fmac_f32_dpp v223, v85, v125 row_ror:1 row_mask:0xf bank_mask:0xf
	v_rcp_f32_e32 v204, v204
	v_fmac_f32_dpp v224, v86, v126 row_ror:1 row_mask:0xf bank_mask:0xf
	v_rcp_f32_e32 v205, v205
	v_fmac_f32_dpp v225, v87, v127 row_ror:1 row_mask:0xf bank_mask:0xf
	v_rcp_f32_e32 v206, v206
	v_fmac_f32_dpp v222, v84, v132 row_ror:2 row_mask:0xf bank_mask:0xf
	v_rcp_f32_e32 v207, v207
; #define LAS __attribute__((address_space(3)))
;     DI void operator()(const AccT& acc, const Unit& u, int wr, int wc, int fr, int fq, LAS unsigned char* ldsx) const {
;     ...
;         for (int n = 0; n < 2; ++n) {
;             const int f = u.pn * 128 + wc * 32 + 16 * n + 4 * fq;
; #pragma unroll
;             for (int ai = 0; ai < 2; ++ai) {
;                 f32x4 hm1 = {0.f, 0.f, 0.f, 0.f}, hm2 = {0.f, 0.f, 0.f, 0.f};
;                 const int sb = 4 * (T - GU_PT) + 2 * ai + wr;
;                 if (prompt) {
;                     if (ai | wr) { const int sai = wr ? ai : ai - 1, swr = wr ^ 1; const LAS float* hp = H + ((sai * 2 + swr) * 4 + wc) * 64 + 16 * n + 4 * fq;
;                         hm2 = *(const LAS f32x4*)hp; hm1 = *(const LAS f32x4*)(hp + 32); }
;                 } else { hm2 = *(const f32x4*)(state + (size_t)(sb * 2) * DFF + f); hm1 = *(const f32x4*)(state + (size_t)(sb * 2 + 1) * DFF + f); }
;                 f32x4 p1 = hm1, p2;
; #pragma unroll
;                 for (int j = 0; j < 4; ++j) p2[j] = fr == 1 ? hm1[j] : hm2[j];
; #pragma unroll
;                 for (int m = 0; m < 4; ++m) {
;                     const f32x4 g = acc[ai][0][m][n] * rs[ai][m];
;                     f32x4 gm1, gm2;
; #pragma unroll
;                     for (int j = 0; j < 4; ++j) {
;                         gm1[j] = __int_as_float(__builtin_amdgcn_update_dpp(__float_as_int(p1[j]), __float_as_int(g[j]), 0x111, 0xf, 0xf, false));
;                         gm2[j] = __int_as_float(__builtin_amdgcn_update_dpp(__float_as_int(p2[j]), __float_as_int(g[j]), 0x112, 0xf, 0xf, false));
;                         if (m < 3) {
;                             p1[j] = __int_as_float(__builtin_amdgcn_update_dpp(0, __float_as_int(g[j]), 0x121, 0xf, 0xf, false));
;                             p2[j] = __int_as_float(__builtin_amdgcn_update_dpp(0, __float_as_int(g[j]), 0x122, 0xf, 0xf, false)); }
;                     }
;                     const f32x4 cv = cb[n] + w0[n] * gm2 + w1[n] * gm1 + w2[n] * g;
;                     const f32x4 up = acc[ai][1][m][n] * rs[ai][m];
;                     f32x4 y;
; #pragma unroll
;                     for (int j = 0; j < 4; ++j) y[j] = cv[j] * __builtin_amdgcn_rcpf(1.f + __builtin_amdgcn_exp2f(-cv[j] * LOG2E)) * up[j];
;                     const int tok = tok0 + 128 * ai + 16 * m;
;                     bool ok = true;
	v_fmac_f32_dpp v223, v85, v133 row_ror:2 row_mask:0xf bank_mask:0xf
	v_pk_mul_f32 v[218:219], v[218:219], v[204:205]
	v_fmac_f32_dpp v224, v86, v134 row_ror:2 row_mask:0xf bank_mask:0xf
	v_pk_mul_f32 v[220:221], v[220:221], v[206:207]
	v_fmac_f32_dpp v225, v87, v135 row_ror:2 row_mask:0xf bank_mask:0xf
	v_pk_mul_f32 v[88:89], v[88:89], v[218:219]
	v_fmac_f32_dpp v222, v92, v160 row_ror:1 row_mask:0xf bank_mask:0xf
	v_pk_mul_f32 v[90:91], v[90:91], v[220:221]
	v_fmac_f32_dpp v223, v93, v161 row_ror:1 row_mask:0xf bank_mask:0xf
	v_cvt_pk_bf16_f32 v88, v88, v89
	v_fmac_f32_dpp v224, v94, v162 row_ror:1 row_mask:0xf bank_mask:0xf
	v_cvt_pk_bf16_f32 v89, v90, v91
	v_fmac_f32_dpp v225, v95, v163 row_ror:1 row_mask:0xf bank_mask:0xf
	v_fmac_f32_dpp v222, v92, v164 row_ror:2 row_mask:0xf bank_mask:0xf
	v_fmac_f32_dpp v223, v93, v165 row_ror:2 row_mask:0xf bank_mask:0xf
	v_fmac_f32_dpp v224, v94, v166 row_ror:2 row_mask:0xf bank_mask:0xf
	v_fmac_f32_dpp v225, v95, v167 row_ror:2 row_mask:0xf bank_mask:0xf
	v_cndmask_b32_e64 v160, 0, v48, s[94:95]
	v_cndmask_b32_e64 v48, v48, 0, s[94:95]
	v_cndmask_b32_e64 v164, 0, v44, s[96:97]
	v_cndmask_b32_e64 v44, v44, 0, s[96:97]
	v_cndmask_b32_e64 v161, 0, v49, s[94:95]
	v_cndmask_b32_e64 v49, v49, 0, s[94:95]
	v_cndmask_b32_e64 v165, 0, v45, s[96:97]
	v_cndmask_b32_e64 v45, v45, 0, s[96:97]
	v_cndmask_b32_e64 v162, 0, v50, s[94:95]
	v_cndmask_b32_e64 v50, v50, 0, s[94:95]
	v_cndmask_b32_e64 v166, 0, v46, s[96:97]
	v_cndmask_b32_e64 v46, v46, 0, s[96:97]
	v_cndmask_b32_e64 v163, 0, v51, s[94:95]
	v_cndmask_b32_e64 v51, v51, 0, s[94:95]
	v_cndmask_b32_e64 v167, 0, v47, s[96:97]
	v_cndmask_b32_e64 v47, v47, 0, s[96:97]
	v_pk_mul_f32 v[204:205], v[222:223], v[184:185] op_sel:[0,1] op_sel_hi:[1,1]
	v_pk_mul_f32 v[76:77], v[76:77], v[214:215] op_sel_hi:[1,0]
	v_pk_mul_f32 v[206:207], v[224:225], v[184:185] op_sel:[0,1] op_sel_hi:[1,1]
	v_pk_mul_f32 v[78:79], v[78:79], v[214:215] op_sel_hi:[1,0]
	v_exp_f32_e32 v204, v204
	v_pk_mul_f32 v[72:73], v[72:73], v[214:215] op_sel_hi:[1,0]
	v_exp_f32_e32 v205, v205
	v_pk_mul_f32 v[74:75], v[74:75], v[214:215] op_sel_hi:[1,0]
	v_exp_f32_e32 v206, v206
	v_pk_fma_f32 v[218:219], v[52:53], v[76:77], v[56:57]
	v_exp_f32_e32 v207, v207
	v_pk_fma_f32 v[220:221], v[54:55], v[78:79], v[58:59]
	v_pk_add_f32 v[204:205], v[204:205], 1.0 op_sel_hi:[1,0]
	v_fmac_f32_dpp v218, v76, v48 row_ror:1 row_mask:0xf bank_mask:0xf
	v_pk_add_f32 v[206:207], v[206:207], 1.0 op_sel_hi:[1,0]
	v_fmac_f32_dpp v219, v77, v49 row_ror:1 row_mask:0xf bank_mask:0xf
	v_rcp_f32_e32 v204, v204
	v_fmac_f32_dpp v220, v78, v50 row_ror:1 row_mask:0xf bank_mask:0xf
	v_rcp_f32_e32 v205, v205
	v_fmac_f32_dpp v221, v79, v51 row_ror:1 row_mask:0xf bank_mask:0xf
	v_rcp_f32_e32 v206, v206
	v_fmac_f32_dpp v218, v76, v44 row_ror:2 row_mask:0xf bank_mask:0xf
	v_rcp_f32_e32 v207, v207
	v_fmac_f32_dpp v219, v77, v45 row_ror:2 row_mask:0xf bank_mask:0xf
	v_pk_mul_f32 v[222:223], v[222:223], v[204:205]
	v_fmac_f32_dpp v220, v78, v46 row_ror:2 row_mask:0xf bank_mask:0xf
	v_pk_mul_f32 v[224:225], v[224:225], v[206:207]
	v_fmac_f32_dpp v221, v79, v47 row_ror:2 row_mask:0xf bank_mask:0xf
	v_pk_mul_f32 v[80:81], v[80:81], v[222:223]
	v_fmac_f32_dpp v218, v248, v160 row_ror:8 row_mask:0xf bank_mask:0xf
	v_pk_mul_f32 v[82:83], v[82:83], v[224:225]
	v_fmac_f32_dpp v219, v249, v161 row_ror:8 row_mask:0xf bank_mask:0xf
	v_cvt_pk_bf16_f32 v80, v80, v81
	v_fmac_f32_dpp v220, v250, v162 row_ror:8 row_mask:0xf bank_mask:0xf
	v_cvt_pk_bf16_f32 v81, v82, v83
	v_fmac_f32_dpp v221, v251, v163 row_ror:8 row_mask:0xf bank_mask:0xf
	v_fmac_f32_dpp v218, v248, v164 row_ror:6 row_mask:0xf bank_mask:0xf
	v_fmac_f32_dpp v219, v249, v165 row_ror:6 row_mask:0xf bank_mask:0xf
	v_fmac_f32_dpp v220, v250, v166 row_ror:6 row_mask:0xf bank_mask:0xf
	v_fmac_f32_dpp v221, v251, v167 row_ror:6 row_mask:0xf bank_mask:0xf
	v_pk_mul_f32 v[204:205], v[218:219], v[184:185] op_sel:[0,1] op_sel_hi:[1,1]
	v_pk_mul_f32 v[68:69], v[68:69], v[210:211] op_sel_hi:[1,0]
	v_pk_mul_f32 v[206:207], v[220:221], v[184:185] op_sel:[0,1] op_sel_hi:[1,1]
	v_pk_mul_f32 v[70:71], v[70:71], v[210:211] op_sel_hi:[1,0]
	v_exp_f32_e32 v204, v204
	v_pk_mul_f32 v[64:65], v[64:65], v[210:211] op_sel_hi:[1,0]
	v_exp_f32_e32 v205, v205
	v_pk_mul_f32 v[66:67], v[66:67], v[210:211] op_sel_hi:[1,0]
	v_exp_f32_e32 v206, v206
	v_pk_fma_f32 v[222:223], v[52:53], v[68:69], v[56:57]
	v_exp_f32_e32 v207, v207
	v_pk_fma_f32 v[224:225], v[54:55], v[70:71], v[58:59]
	v_pk_add_f32 v[204:205], v[204:205], 1.0 op_sel_hi:[1,0]
	v_fmac_f32_dpp v222, v68, v48 row_ror:1 row_mask:0xf bank_mask:0xf
	v_pk_add_f32 v[206:207], v[206:207], 1.0 op_sel_hi:[1,0]
	v_fmac_f32_dpp v223, v69, v49 row_ror:1 row_mask:0xf bank_mask:0xf
	v_rcp_f32_e32 v204, v204
	v_fmac_f32_dpp v224, v70, v50 row_ror:1 row_mask:0xf bank_mask:0xf
	v_rcp_f32_e32 v205, v205
	v_fmac_f32_dpp v225, v71, v51 row_ror:1 row_mask:0xf bank_mask:0xf
	v_rcp_f32_e32 v206, v206
	v_fmac_f32_dpp v222, v68, v44 row_ror:2 row_mask:0xf bank_mask:0xf
	v_rcp_f32_e32 v207, v207
	v_fmac_f32_dpp v223, v69, v45 row_ror:2 row_mask:0xf bank_mask:0xf
	v_pk_mul_f32 v[218:219], v[218:219], v[204:205]
	v_fmac_f32_dpp v224, v70, v46 row_ror:2 row_mask:0xf bank_mask:0xf
	v_pk_mul_f32 v[220:221], v[220:221], v[206:207]
	v_fmac_f32_dpp v225, v71, v47 row_ror:2 row_mask:0xf bank_mask:0xf
	v_pk_mul_f32 v[72:73], v[72:73], v[218:219]
	v_fmac_f32_dpp v222, v76, v160 row_ror:1 row_mask:0xf bank_mask:0xf
	v_pk_mul_f32 v[74:75], v[74:75], v[220:221]
	v_fmac_f32_dpp v223, v77, v161 row_ror:1 row_mask:0xf bank_mask:0xf
	v_cvt_pk_bf16_f32 v154, v72, v73
; DI u32x2 pk4(f32x4 v) { u32x2 r; r.x = pk2(v[0], v[1]); r.y = pk2(v[2], v[3]); return r; }
;     DI void operator()(const AccT& acc, const Unit& u, int wr, int wc, int fr, int fq, LAS unsigned char* ldsx) const {
;     ...
;                 for (int m = 0; m < 4; ++m) {
;                     const f32x4 g = acc[ai][0][m][n] * rs[ai][m];
;                     f32x4 gm1, gm2;
; #pragma unroll
;                     for (int j = 0; j < 4; ++j) {
;                         gm1[j] = __int_as_float(__builtin_amdgcn_update_dpp(__float_as_int(p1[j]), __float_as_int(g[j]), 0x111, 0xf, 0xf, false));
;                         gm2[j] = __int_as_float(__builtin_amdgcn_update_dpp(__float_as_int(p2[j]), __float_as_int(g[j]), 0x112, 0xf, 0xf, false));
;                         if (m < 3) {
;                             p1[j] = __int_as_float(__builtin_amdgcn_update_dpp(0, __float_as_int(g[j]), 0x121, 0xf, 0xf, false));
;                             p2[j] = __int_as_float(__builtin_amdgcn_update_dpp(0, __float_as_int(g[j]), 0x122, 0xf, 0xf, false)); }
;                     }
;                     const f32x4 cv = cb[n] + w0[n] * gm2 + w1[n] * gm1 + w2[n] * g;
;                     const f32x4 up = acc[ai][1][m][n] * rs[ai][m];
;                     f32x4 y;
; #pragma unroll
;                     for (int j = 0; j < 4; ++j) y[j] = cv[j] * __builtin_amdgcn_rcpf(1.f + __builtin_amdgcn_exp2f(-cv[j] * LOG2E)) * up[j];
;                     const int tok = tok0 + 128 * ai + 16 * m;
;                     bool ok = true;
;                     if (prompt && ai == 0 && m == 0) ok = (64 * wr + fr) >= 2;
;                     if (lastT) ok = ok && tok < SEQ;
;                     if (ok) *(u32x2*)(Y + ((unsigned)tok * (unsigned)DFF + (unsigned)f)) = pk4(y);
	v_fmac_f32_dpp v224, v78, v162 row_ror:1 row_mask:0xf bank_mask:0xf
	v_cvt_pk_bf16_f32 v155, v74, v75
	v_fmac_f32_dpp v225, v79, v163 row_ror:1 row_mask:0xf bank_mask:0xf
	v_fmac_f32_dpp v222, v76, v164 row_ror:2 row_mask:0xf bank_mask:0xf
	v_fmac_f32_dpp v223, v77, v165 row_ror:2 row_mask:0xf bank_mask:0xf
	v_fmac_f32_dpp v224, v78, v166 row_ror:2 row_mask:0xf bank_mask:0xf
	v_fmac_f32_dpp v225, v79, v167 row_ror:2 row_mask:0xf bank_mask:0xf
	s_nop 1
	v_permlane16_swap_b32_e32 v152, v154
	v_permlane16_swap_b32_e32 v153, v155
	s_and_saveexec_b64 s[28:29], s[60:61]
	global_store_dwordx4 v213, v[152:155], s[46:47]
	s_mov_b64 exec, s[28:29]
	s_add_u32 s46, s46, 0x16000
	s_addc_u32 s47, s47, 0
	v_pk_mul_f32 v[204:205], v[222:223], v[184:185] op_sel:[0,1] op_sel_hi:[1,1]
	v_pk_mul_f32 v[60:61], v[60:61], v[208:209] op_sel_hi:[1,0]
	v_pk_mul_f32 v[206:207], v[224:225], v[184:185] op_sel:[0,1] op_sel_hi:[1,1]
	v_pk_mul_f32 v[62:63], v[62:63], v[208:209] op_sel_hi:[1,0]
	v_exp_f32_e32 v204, v204
	v_pk_mul_f32 v[40:41], v[40:41], v[208:209] op_sel_hi:[1,0]
	v_exp_f32_e32 v205, v205
	v_pk_mul_f32 v[42:43], v[42:43], v[208:209] op_sel_hi:[1,0]
	v_exp_f32_e32 v206, v206
	v_pk_fma_f32 v[218:219], v[52:53], v[60:61], v[56:57]
	v_exp_f32_e32 v207, v207
	v_pk_fma_f32 v[220:221], v[54:55], v[62:63], v[58:59]
	v_pk_add_f32 v[204:205], v[204:205], 1.0 op_sel_hi:[1,0]
	v_fmac_f32_dpp v218, v60, v48 row_ror:1 row_mask:0xf bank_mask:0xf
	v_pk_add_f32 v[206:207], v[206:207], 1.0 op_sel_hi:[1,0]
	v_fmac_f32_dpp v219, v61, v49 row_ror:1 row_mask:0xf bank_mask:0xf
	v_rcp_f32_e32 v204, v204
	v_fmac_f32_dpp v220, v62, v50 row_ror:1 row_mask:0xf bank_mask:0xf
	v_rcp_f32_e32 v205, v205
	v_fmac_f32_dpp v221, v63, v51 row_ror:1 row_mask:0xf bank_mask:0xf
	v_rcp_f32_e32 v206, v206
	v_fmac_f32_dpp v218, v60, v44 row_ror:2 row_mask:0xf bank_mask:0xf
	v_rcp_f32_e32 v207, v207
	v_fmac_f32_dpp v219, v61, v45 row_ror:2 row_mask:0xf bank_mask:0xf
	v_pk_mul_f32 v[222:223], v[222:223], v[204:205]
	v_fmac_f32_dpp v220, v62, v46 row_ror:2 row_mask:0xf bank_mask:0xf
	v_pk_mul_f32 v[224:225], v[224:225], v[206:207]
	v_fmac_f32_dpp v221, v63, v47 row_ror:2 row_mask:0xf bank_mask:0xf
	v_pk_mul_f32 v[64:65], v[64:65], v[222:223]
	v_fmac_f32_dpp v218, v68, v160 row_ror:1 row_mask:0xf bank_mask:0xf
	v_pk_mul_f32 v[66:67], v[66:67], v[224:225]
	v_fmac_f32_dpp v219, v69, v161 row_ror:1 row_mask:0xf bank_mask:0xf
	v_cvt_pk_bf16_f32 v146, v64, v65
	v_fmac_f32_dpp v220, v70, v162 row_ror:1 row_mask:0xf bank_mask:0xf
	v_cvt_pk_bf16_f32 v147, v66, v67
	v_fmac_f32_dpp v221, v71, v163 row_ror:1 row_mask:0xf bank_mask:0xf
	v_fmac_f32_dpp v218, v68, v164 row_ror:2 row_mask:0xf bank_mask:0xf
	v_fmac_f32_dpp v219, v69, v165 row_ror:2 row_mask:0xf bank_mask:0xf
	v_fmac_f32_dpp v220, v70, v166 row_ror:2 row_mask:0xf bank_mask:0xf
	v_fmac_f32_dpp v221, v71, v167 row_ror:2 row_mask:0xf bank_mask:0xf
	s_nop 1
	v_permlane16_swap_b32_e32 v144, v146
	v_permlane16_swap_b32_e32 v145, v147
	s_and_saveexec_b64 s[28:29], s[62:63]
	global_store_dwordx4 v213, v[144:147], s[46:47]
	s_mov_b64 exec, s[28:29]
	s_add_u32 s46, s46, 0x16000
	s_addc_u32 s47, s47, 0
	v_pk_mul_f32 v[204:205], v[218:219], v[184:185] op_sel:[0,1] op_sel_hi:[1,1]
	v_pk_mul_f32 v[36:37], v[36:37], v[202:203] op_sel_hi:[1,0]
	v_pk_mul_f32 v[206:207], v[220:221], v[184:185] op_sel:[0,1] op_sel_hi:[1,1]
	v_pk_mul_f32 v[38:39], v[38:39], v[202:203] op_sel_hi:[1,0]
	v_exp_f32_e32 v204, v204
	v_pk_mul_f32 v[32:33], v[32:33], v[202:203] op_sel_hi:[1,0]
	v_exp_f32_e32 v205, v205
	v_pk_mul_f32 v[34:35], v[34:35], v[202:203] op_sel_hi:[1,0]
	v_exp_f32_e32 v206, v206
	v_pk_fma_f32 v[222:223], v[52:53], v[36:37], v[56:57]
	v_exp_f32_e32 v207, v207
	v_pk_fma_f32 v[224:225], v[54:55], v[38:39], v[58:59]
	v_pk_add_f32 v[204:205], v[204:205], 1.0 op_sel_hi:[1,0]
	v_fmac_f32_dpp v222, v36, v48 row_ror:1 row_mask:0xf bank_mask:0xf
	v_pk_add_f32 v[206:207], v[206:207], 1.0 op_sel_hi:[1,0]
	v_fmac_f32_dpp v223, v37, v49 row_ror:1 row_mask:0xf bank_mask:0xf
	v_rcp_f32_e32 v204, v204
	v_fmac_f32_dpp v224, v38, v50 row_ror:1 row_mask:0xf bank_mask:0xf
	v_rcp_f32_e32 v205, v205
	v_fmac_f32_dpp v225, v39, v51 row_ror:1 row_mask:0xf bank_mask:0xf
	v_rcp_f32_e32 v206, v206
	v_fmac_f32_dpp v222, v36, v44 row_ror:2 row_mask:0xf bank_mask:0xf
	v_rcp_f32_e32 v207, v207
	v_fmac_f32_dpp v223, v37, v45 row_ror:2 row_mask:0xf bank_mask:0xf
	v_pk_mul_f32 v[218:219], v[218:219], v[204:205]
	v_fmac_f32_dpp v224, v38, v46 row_ror:2 row_mask:0xf bank_mask:0xf
	v_pk_mul_f32 v[220:221], v[220:221], v[206:207]
	v_fmac_f32_dpp v225, v39, v47 row_ror:2 row_mask:0xf bank_mask:0xf
	v_pk_mul_f32 v[40:41], v[40:41], v[218:219]
	v_fmac_f32_dpp v222, v60, v160 row_ror:1 row_mask:0xf bank_mask:0xf
	v_pk_mul_f32 v[42:43], v[42:43], v[220:221]
	v_fmac_f32_dpp v223, v61, v161 row_ror:1 row_mask:0xf bank_mask:0xf
	v_cvt_pk_bf16_f32 v122, v40, v41
	v_fmac_f32_dpp v224, v62, v162 row_ror:1 row_mask:0xf bank_mask:0xf
	v_cvt_pk_bf16_f32 v123, v42, v43
	v_fmac_f32_dpp v225, v63, v163 row_ror:1 row_mask:0xf bank_mask:0xf
	v_fmac_f32_dpp v222, v60, v164 row_ror:2 row_mask:0xf bank_mask:0xf
	v_fmac_f32_dpp v223, v61, v165 row_ror:2 row_mask:0xf bank_mask:0xf
	v_fmac_f32_dpp v224, v62, v166 row_ror:2 row_mask:0xf bank_mask:0xf
	v_fmac_f32_dpp v225, v63, v167 row_ror:2 row_mask:0xf bank_mask:0xf
	s_nop 1
	v_permlane16_swap_b32_e32 v120, v122
	v_permlane16_swap_b32_e32 v121, v123
	s_and_saveexec_b64 s[28:29], s[64:65]
	global_store_dwordx4 v213, v[120:123], s[46:47]
	s_mov_b64 exec, s[28:29]
	s_add_u32 s46, s46, 0x16000
	s_addc_u32 s47, s47, 0
	v_pk_mul_f32 v[204:205], v[222:223], v[184:185] op_sel:[0,1] op_sel_hi:[1,1]
; DI u32x2 pk4(f32x4 v) { u32x2 r; r.x = pk2(v[0], v[1]); r.y = pk2(v[2], v[3]); return r; }
;     DI void operator()(const AccT& acc, const Unit& u, int wr, int wc, int fr, int fq, LAS unsigned char* ldsx) const {
;     ...
;                 for (int m = 0; m < 4; ++m) {
;                     const f32x4 g = acc[ai][0][m][n] * rs[ai][m];
;                     f32x4 gm1, gm2;
; #pragma unroll
;                     for (int j = 0; j < 4; ++j) {
;                         gm1[j] = __int_as_float(__builtin_amdgcn_update_dpp(__float_as_int(p1[j]), __float_as_int(g[j]), 0x111, 0xf, 0xf, false));
;                         gm2[j] = __int_as_float(__builtin_amdgcn_update_dpp(__float_as_int(p2[j]), __float_as_int(g[j]), 0x112, 0xf, 0xf, false));
;                         if (m < 3) {
;                             p1[j] = __int_as_float(__builtin_amdgcn_update_dpp(0, __float_as_int(g[j]), 0x121, 0xf, 0xf, false));
;                             p2[j] = __int_as_float(__builtin_amdgcn_update_dpp(0, __float_as_int(g[j]), 0x122, 0xf, 0xf, false)); }
;                     }
;                     const f32x4 cv = cb[n] + w0[n] * gm2 + w1[n] * gm1 + w2[n] * g;
;                     const f32x4 up = acc[ai][1][m][n] * rs[ai][m];
;                     f32x4 y;
; #pragma unroll
;                     for (int j = 0; j < 4; ++j) y[j] = cv[j] * __builtin_amdgcn_rcpf(1.f + __builtin_amdgcn_exp2f(-cv[j] * LOG2E)) * up[j];
;                     const int tok = tok0 + 128 * ai + 16 * m;
;                     bool ok = true;
;                     if (prompt && ai == 0 && m == 0) ok = (64 * wr + fr) >= 2;
;                     if (lastT) ok = ok && tok < SEQ;
;                     if (ok) *(u32x2*)(Y + ((unsigned)tok * (unsigned)DFF + (unsigned)f)) = pk4(y);
	v_pk_mul_f32 v[28:29], v[28:29], v[200:201] op_sel_hi:[1,0]
	v_pk_mul_f32 v[206:207], v[224:225], v[184:185] op_sel:[0,1] op_sel_hi:[1,1]
	v_pk_mul_f32 v[30:31], v[30:31], v[200:201] op_sel_hi:[1,0]
	v_exp_f32_e32 v204, v204
	v_pk_mul_f32 v[24:25], v[24:25], v[200:201] op_sel_hi:[1,0]
	v_exp_f32_e32 v205, v205
	v_pk_mul_f32 v[26:27], v[26:27], v[200:201] op_sel_hi:[1,0]
	v_exp_f32_e32 v206, v206
	v_pk_fma_f32 v[218:219], v[52:53], v[28:29], v[56:57]
	v_exp_f32_e32 v207, v207
	v_pk_fma_f32 v[220:221], v[54:55], v[30:31], v[58:59]
	v_pk_add_f32 v[204:205], v[204:205], 1.0 op_sel_hi:[1,0]
	v_fmac_f32_dpp v218, v28, v48 row_ror:1 row_mask:0xf bank_mask:0xf
	v_pk_add_f32 v[206:207], v[206:207], 1.0 op_sel_hi:[1,0]
	v_fmac_f32_dpp v219, v29, v49 row_ror:1 row_mask:0xf bank_mask:0xf
	v_rcp_f32_e32 v204, v204
	v_fmac_f32_dpp v220, v30, v50 row_ror:1 row_mask:0xf bank_mask:0xf
	v_rcp_f32_e32 v205, v205
	v_fmac_f32_dpp v221, v31, v51 row_ror:1 row_mask:0xf bank_mask:0xf
	v_rcp_f32_e32 v206, v206
	v_fmac_f32_dpp v218, v28, v44 row_ror:2 row_mask:0xf bank_mask:0xf
	v_rcp_f32_e32 v207, v207
	v_fmac_f32_dpp v219, v29, v45 row_ror:2 row_mask:0xf bank_mask:0xf
	v_pk_mul_f32 v[222:223], v[222:223], v[204:205]
	v_fmac_f32_dpp v220, v30, v46 row_ror:2 row_mask:0xf bank_mask:0xf
	v_pk_mul_f32 v[224:225], v[224:225], v[206:207]
	v_fmac_f32_dpp v221, v31, v47 row_ror:2 row_mask:0xf bank_mask:0xf
	v_pk_mul_f32 v[32:33], v[32:33], v[222:223]
	v_fmac_f32_dpp v218, v248, v160 row_ror:4 row_mask:0xf bank_mask:0xf
	v_pk_mul_f32 v[34:35], v[34:35], v[224:225]
	v_fmac_f32_dpp v219, v249, v161 row_ror:4 row_mask:0xf bank_mask:0xf
	v_cvt_pk_bf16_f32 v114, v32, v33
	v_fmac_f32_dpp v220, v250, v162 row_ror:4 row_mask:0xf bank_mask:0xf
	v_cvt_pk_bf16_f32 v115, v34, v35
	v_fmac_f32_dpp v221, v251, v163 row_ror:4 row_mask:0xf bank_mask:0xf
	v_fmac_f32_dpp v218, v248, v164 row_ror:2 row_mask:0xf bank_mask:0xf
	v_fmac_f32_dpp v219, v249, v165 row_ror:2 row_mask:0xf bank_mask:0xf
	v_fmac_f32_dpp v220, v250, v166 row_ror:2 row_mask:0xf bank_mask:0xf
	v_fmac_f32_dpp v221, v251, v167 row_ror:2 row_mask:0xf bank_mask:0xf
	s_nop 1
	v_permlane16_swap_b32_e32 v112, v114
	v_permlane16_swap_b32_e32 v113, v115
	s_and_saveexec_b64 s[28:29], s[66:67]
	global_store_dwordx4 v213, v[112:115], s[46:47]
	s_mov_b64 exec, s[28:29]
	s_add_u32 s46, s46, 0x6e000
	s_addc_u32 s47, s47, 0
	v_pk_mul_f32 v[204:205], v[218:219], v[184:185] op_sel:[0,1] op_sel_hi:[1,1]
	v_pk_mul_f32 v[20:21], v[20:21], v[192:193] op_sel_hi:[1,0]
	v_pk_mul_f32 v[206:207], v[220:221], v[184:185] op_sel:[0,1] op_sel_hi:[1,1]
	v_pk_mul_f32 v[22:23], v[22:23], v[192:193] op_sel_hi:[1,0]
	v_exp_f32_e32 v204, v204
	v_pk_mul_f32 v[16:17], v[16:17], v[192:193] op_sel_hi:[1,0]
	v_exp_f32_e32 v205, v205
	v_pk_mul_f32 v[18:19], v[18:19], v[192:193] op_sel_hi:[1,0]
	v_exp_f32_e32 v206, v206
	v_pk_fma_f32 v[222:223], v[52:53], v[20:21], v[56:57]
	v_exp_f32_e32 v207, v207
	v_pk_fma_f32 v[224:225], v[54:55], v[22:23], v[58:59]
	v_pk_add_f32 v[204:205], v[204:205], 1.0 op_sel_hi:[1,0]
	v_fmac_f32_dpp v222, v20, v48 row_ror:1 row_mask:0xf bank_mask:0xf
	v_pk_add_f32 v[206:207], v[206:207], 1.0 op_sel_hi:[1,0]
	v_fmac_f32_dpp v223, v21, v49 row_ror:1 row_mask:0xf bank_mask:0xf
	v_rcp_f32_e32 v204, v204
	v_fmac_f32_dpp v224, v22, v50 row_ror:1 row_mask:0xf bank_mask:0xf
	v_rcp_f32_e32 v205, v205
	v_fmac_f32_dpp v225, v23, v51 row_ror:1 row_mask:0xf bank_mask:0xf
	v_rcp_f32_e32 v206, v206
	v_fmac_f32_dpp v222, v20, v44 row_ror:2 row_mask:0xf bank_mask:0xf
	v_rcp_f32_e32 v207, v207
	v_fmac_f32_dpp v223, v21, v45 row_ror:2 row_mask:0xf bank_mask:0xf
	v_pk_mul_f32 v[218:219], v[218:219], v[204:205]
	v_fmac_f32_dpp v224, v22, v46 row_ror:2 row_mask:0xf bank_mask:0xf
	v_pk_mul_f32 v[220:221], v[220:221], v[206:207]
	v_fmac_f32_dpp v225, v23, v47 row_ror:2 row_mask:0xf bank_mask:0xf
	v_pk_mul_f32 v[24:25], v[24:25], v[218:219]
	v_fmac_f32_dpp v222, v28, v160 row_ror:1 row_mask:0xf bank_mask:0xf
	v_pk_mul_f32 v[26:27], v[26:27], v[220:221]
	v_fmac_f32_dpp v223, v29, v161 row_ror:1 row_mask:0xf bank_mask:0xf
	v_cvt_pk_bf16_f32 v106, v24, v25
	v_fmac_f32_dpp v224, v30, v162 row_ror:1 row_mask:0xf bank_mask:0xf
	v_cvt_pk_bf16_f32 v107, v26, v27
	v_fmac_f32_dpp v225, v31, v163 row_ror:1 row_mask:0xf bank_mask:0xf
	v_fmac_f32_dpp v222, v28, v164 row_ror:2 row_mask:0xf bank_mask:0xf
	v_fmac_f32_dpp v223, v29, v165 row_ror:2 row_mask:0xf bank_mask:0xf
	v_fmac_f32_dpp v224, v30, v166 row_ror:2 row_mask:0xf bank_mask:0xf
	v_fmac_f32_dpp v225, v31, v167 row_ror:2 row_mask:0xf bank_mask:0xf
	s_nop 1
	v_permlane16_swap_b32_e32 v104, v106
	v_permlane16_swap_b32_e32 v105, v107
	s_and_saveexec_b64 s[28:29], s[68:69]
	global_store_dwordx4 v213, v[104:107], s[46:47]
	s_mov_b64 exec, s[28:29]
	s_add_u32 s46, s46, 0x16000
	s_addc_u32 s47, s47, 0
	v_pk_mul_f32 v[204:205], v[222:223], v[184:185] op_sel:[0,1] op_sel_hi:[1,1]
	v_pk_mul_f32 v[12:13], v[12:13], v[190:191] op_sel_hi:[1,0]
	v_pk_mul_f32 v[206:207], v[224:225], v[184:185] op_sel:[0,1] op_sel_hi:[1,1]
	v_pk_mul_f32 v[14:15], v[14:15], v[190:191] op_sel_hi:[1,0]
	v_exp_f32_e32 v204, v204
	v_pk_mul_f32 v[8:9], v[8:9], v[190:191] op_sel_hi:[1,0]
	v_exp_f32_e32 v205, v205
	v_pk_mul_f32 v[10:11], v[10:11], v[190:191] op_sel_hi:[1,0]
	v_exp_f32_e32 v206, v206
	v_pk_fma_f32 v[218:219], v[52:53], v[12:13], v[56:57]
	v_exp_f32_e32 v207, v207
	v_pk_fma_f32 v[220:221], v[54:55], v[14:15], v[58:59]
	v_pk_add_f32 v[204:205], v[204:205], 1.0 op_sel_hi:[1,0]
	v_fmac_f32_dpp v218, v12, v48 row_ror:1 row_mask:0xf bank_mask:0xf
	v_pk_add_f32 v[206:207], v[206:207], 1.0 op_sel_hi:[1,0]
	v_fmac_f32_dpp v219, v13, v49 row_ror:1 row_mask:0xf bank_mask:0xf
; DI u32x2 pk4(f32x4 v) { u32x2 r; r.x = pk2(v[0], v[1]); r.y = pk2(v[2], v[3]); return r; }
;     DI void operator()(const AccT& acc, const Unit& u, int wr, int wc, int fr, int fq, LAS unsigned char* ldsx) const {
;     ...
;                 for (int m = 0; m < 4; ++m) {
;                     const f32x4 g = acc[ai][0][m][n] * rs[ai][m];
;                     f32x4 gm1, gm2;
; #pragma unroll
;                     for (int j = 0; j < 4; ++j) {
;                         gm1[j] = __int_as_float(__builtin_amdgcn_update_dpp(__float_as_int(p1[j]), __float_as_int(g[j]), 0x111, 0xf, 0xf, false));
;                         gm2[j] = __int_as_float(__builtin_amdgcn_update_dpp(__float_as_int(p2[j]), __float_as_int(g[j]), 0x112, 0xf, 0xf, false));
;                         if (m < 3) {
;                             p1[j] = __int_as_float(__builtin_amdgcn_update_dpp(0, __float_as_int(g[j]), 0x121, 0xf, 0xf, false));
;                             p2[j] = __int_as_float(__builtin_amdgcn_update_dpp(0, __float_as_int(g[j]), 0x122, 0xf, 0xf, false)); }
;                     }
;                     const f32x4 cv = cb[n] + w0[n] * gm2 + w1[n] * gm1 + w2[n] * g;
;                     const f32x4 up = acc[ai][1][m][n] * rs[ai][m];
;                     f32x4 y;
; #pragma unroll
;                     for (int j = 0; j < 4; ++j) y[j] = cv[j] * __builtin_amdgcn_rcpf(1.f + __builtin_amdgcn_exp2f(-cv[j] * LOG2E)) * up[j];
;                     const int tok = tok0 + 128 * ai + 16 * m;
;                     bool ok = true;
;                     if (prompt && ai == 0 && m == 0) ok = (64 * wr + fr) >= 2;
;                     if (lastT) ok = ok && tok < SEQ;
;                     if (ok) *(u32x2*)(Y + ((unsigned)tok * (unsigned)DFF + (unsigned)f)) = pk4(y);
;                     if (lastT) { if (tok == SEQ - 2 || tok == SEQ - 1) *(f32x4*)(out + OFF_CVP + (size_t)(tok - (SEQ - 2)) * DFF + f) = g; }
;                     if (!prompt && m == 3 && fr >= 14) *(f32x4*)(out + OFF_CVS + (size_t)(sb * 2 + (fr - 14)) * DFF + f) = g;
	v_rcp_f32_e32 v204, v204
	v_fmac_f32_dpp v220, v14, v50 row_ror:1 row_mask:0xf bank_mask:0xf
	v_rcp_f32_e32 v205, v205
	v_fmac_f32_dpp v221, v15, v51 row_ror:1 row_mask:0xf bank_mask:0xf
	v_rcp_f32_e32 v206, v206
	v_fmac_f32_dpp v218, v12, v44 row_ror:2 row_mask:0xf bank_mask:0xf
	v_rcp_f32_e32 v207, v207
	v_fmac_f32_dpp v219, v13, v45 row_ror:2 row_mask:0xf bank_mask:0xf
	v_pk_mul_f32 v[222:223], v[222:223], v[204:205]
	v_fmac_f32_dpp v220, v14, v46 row_ror:2 row_mask:0xf bank_mask:0xf
	v_pk_mul_f32 v[224:225], v[224:225], v[206:207]
	v_fmac_f32_dpp v221, v15, v47 row_ror:2 row_mask:0xf bank_mask:0xf
	v_pk_mul_f32 v[16:17], v[16:17], v[222:223]
	v_fmac_f32_dpp v218, v20, v160 row_ror:1 row_mask:0xf bank_mask:0xf
	v_pk_mul_f32 v[18:19], v[18:19], v[224:225]
	v_fmac_f32_dpp v219, v21, v161 row_ror:1 row_mask:0xf bank_mask:0xf
	v_cvt_pk_bf16_f32 v98, v16, v17
	v_fmac_f32_dpp v220, v22, v162 row_ror:1 row_mask:0xf bank_mask:0xf
	v_cvt_pk_bf16_f32 v99, v18, v19
	v_fmac_f32_dpp v221, v23, v163 row_ror:1 row_mask:0xf bank_mask:0xf
	v_fmac_f32_dpp v218, v20, v164 row_ror:2 row_mask:0xf bank_mask:0xf
	v_fmac_f32_dpp v219, v21, v165 row_ror:2 row_mask:0xf bank_mask:0xf
	v_fmac_f32_dpp v220, v22, v166 row_ror:2 row_mask:0xf bank_mask:0xf
	v_fmac_f32_dpp v221, v23, v167 row_ror:2 row_mask:0xf bank_mask:0xf
	s_nop 1
	v_permlane16_swap_b32_e32 v96, v98
	v_permlane16_swap_b32_e32 v97, v99
	s_and_saveexec_b64 s[28:29], s[70:71]
	global_store_dwordx4 v213, v[96:99], s[46:47]
	s_mov_b64 exec, s[28:29]
	s_add_u32 s46, s46, 0x16000
	s_addc_u32 s47, s47, 0
	v_pk_mul_f32 v[204:205], v[218:219], v[184:185] op_sel:[0,1] op_sel_hi:[1,1]
	v_pk_mul_f32 v[4:5], v[4:5], v[184:185] op_sel_hi:[1,0]
	v_pk_mul_f32 v[206:207], v[220:221], v[184:185] op_sel:[0,1] op_sel_hi:[1,1]
	v_pk_mul_f32 v[6:7], v[6:7], v[184:185] op_sel_hi:[1,0]
	v_exp_f32_e32 v204, v204
	v_pk_mul_f32 v[0:1], v[0:1], v[184:185] op_sel_hi:[1,0]
	v_exp_f32_e32 v205, v205
	v_pk_mul_f32 v[2:3], v[2:3], v[184:185] op_sel_hi:[1,0]
	v_exp_f32_e32 v206, v206
	v_pk_fma_f32 v[222:223], v[52:53], v[4:5], v[56:57]
	v_exp_f32_e32 v207, v207
	v_pk_fma_f32 v[224:225], v[54:55], v[6:7], v[58:59]
	v_pk_add_f32 v[204:205], v[204:205], 1.0 op_sel_hi:[1,0]
	v_fmac_f32_dpp v222, v4, v48 row_ror:1 row_mask:0xf bank_mask:0xf
	v_pk_add_f32 v[206:207], v[206:207], 1.0 op_sel_hi:[1,0]
	v_fmac_f32_dpp v223, v5, v49 row_ror:1 row_mask:0xf bank_mask:0xf
	v_rcp_f32_e32 v204, v204
	v_fmac_f32_dpp v224, v6, v50 row_ror:1 row_mask:0xf bank_mask:0xf
	v_rcp_f32_e32 v205, v205
	v_fmac_f32_dpp v225, v7, v51 row_ror:1 row_mask:0xf bank_mask:0xf
	v_rcp_f32_e32 v206, v206
	v_fmac_f32_dpp v222, v4, v44 row_ror:2 row_mask:0xf bank_mask:0xf
	v_rcp_f32_e32 v207, v207
	v_fmac_f32_dpp v223, v5, v45 row_ror:2 row_mask:0xf bank_mask:0xf
	v_pk_mul_f32 v[218:219], v[218:219], v[204:205]
	v_fmac_f32_dpp v224, v6, v46 row_ror:2 row_mask:0xf bank_mask:0xf
	v_pk_mul_f32 v[220:221], v[220:221], v[206:207]
	v_fmac_f32_dpp v225, v7, v47 row_ror:2 row_mask:0xf bank_mask:0xf
	v_pk_mul_f32 v[8:9], v[8:9], v[218:219]
	v_fmac_f32_dpp v222, v12, v160 row_ror:1 row_mask:0xf bank_mask:0xf
	v_pk_mul_f32 v[10:11], v[10:11], v[220:221]
	v_fmac_f32_dpp v223, v13, v161 row_ror:1 row_mask:0xf bank_mask:0xf
	v_cvt_pk_bf16_f32 v90, v8, v9
	v_fmac_f32_dpp v224, v14, v162 row_ror:1 row_mask:0xf bank_mask:0xf
	v_cvt_pk_bf16_f32 v91, v10, v11
	v_fmac_f32_dpp v225, v15, v163 row_ror:1 row_mask:0xf bank_mask:0xf
	v_fmac_f32_dpp v222, v12, v164 row_ror:2 row_mask:0xf bank_mask:0xf
	v_fmac_f32_dpp v223, v13, v165 row_ror:2 row_mask:0xf bank_mask:0xf
	v_fmac_f32_dpp v224, v14, v166 row_ror:2 row_mask:0xf bank_mask:0xf
	v_fmac_f32_dpp v225, v15, v167 row_ror:2 row_mask:0xf bank_mask:0xf
	s_nop 1
	v_permlane16_swap_b32_e32 v88, v90
	v_permlane16_swap_b32_e32 v89, v91
	s_and_saveexec_b64 s[28:29], s[72:73]
	global_store_dwordx4 v213, v[88:91], s[46:47]
	s_mov_b64 exec, s[28:29]
	s_add_u32 s46, s46, 0x16000
	s_addc_u32 s47, s47, 0
	v_pk_mul_f32 v[204:205], v[222:223], v[184:185] op_sel:[0,1] op_sel_hi:[1,1]
	v_pk_mul_f32 v[206:207], v[224:225], v[184:185] op_sel:[0,1] op_sel_hi:[1,1]
	v_exp_f32_e32 v204, v204
	v_exp_f32_e32 v205, v205
	v_exp_f32_e32 v206, v206
	v_exp_f32_e32 v207, v207
	v_pk_add_f32 v[204:205], v[204:205], 1.0 op_sel_hi:[1,0]
	v_pk_add_f32 v[206:207], v[206:207], 1.0 op_sel_hi:[1,0]
	v_rcp_f32_e32 v204, v204
	v_rcp_f32_e32 v205, v205
	v_rcp_f32_e32 v206, v206
	v_rcp_f32_e32 v207, v207
	v_pk_mul_f32 v[222:223], v[222:223], v[204:205]
	v_pk_mul_f32 v[224:225], v[224:225], v[206:207]
	v_pk_mul_f32 v[0:1], v[0:1], v[222:223]
	v_pk_mul_f32 v[2:3], v[2:3], v[224:225]
	v_cvt_pk_bf16_f32 v82, v0, v1
	v_cvt_pk_bf16_f32 v83, v2, v3
	s_nop 1
	v_permlane16_swap_b32_e32 v80, v82
	v_permlane16_swap_b32_e32 v81, v83
	s_and_saveexec_b64 s[28:29], s[74:75]
	global_store_dwordx4 v213, v[80:83], s[46:47]
	s_mov_b64 exec, s[28:29]
	s_cmp_gt_i32 s42, 64
	s_cbranch_scc0 .Lgu_nocvs
	v_readlane_b32 s30, v252, 0
	v_readlane_b32 s31, v252, 1
	s_lshl_b32 s23, s42, 2
	s_add_i32 s23, s36, s23
	s_lshl_b32 s23, s23, 1
	s_movk_i32 s76, 0x2c00
	v_add_u32_e32 v186, s23, v233
	v_mad_i64_i32 v[186:187], s[34:35], v186, s76, 0
	v_lshl_add_u64 v[186:187], s[14:15], 0, v[186:187]
	v_lshl_add_u64 v[186:187], v[216:217], 2, v[186:187]
	s_and_saveexec_b64 s[28:29], s[30:31]
	global_store_dwordx4 v[186:187], v[116:119], off
	global_store_dwordx4 v[186:187], v[36:39], off offset:64
	s_mov_b64 exec, s[28:29]
	s_add_i32 s23, s23, 4
	v_add_u32_e32 v186, s23, v233
	v_mad_i64_i32 v[186:187], s[34:35], v186, s76, 0
	v_lshl_add_u64 v[186:187], s[14:15], 0, v[186:187]
	v_lshl_add_u64 v[186:187], v[216:217], 2, v[186:187]
	s_and_saveexec_b64 s[28:29], s[30:31]
	global_store_dwordx4 v[186:187], v[84:87], off
	global_store_dwordx4 v[186:187], v[4:7], off offset:64
	s_mov_b64 exec, s[28:29]
